# E_GU pair units remapped: WG j and j^1 share the A row panel (adjacent column pairs)
# speedup vs baseline: 1.1014x; 1.0011x over previous
.LBB0_116:
	s_andn2_b64 vcc, exec, s[0:1]
	s_cbranch_vccnz .LBB0_143
	s_mov_b32 s63, 2
	s_mov_b32 s62, 0
	s_load_dword s0, s[96:97], 0x0
	s_and_b32 s22, s74, 7
	s_waitcnt lgkmcnt(0)
	s_lshr_b32 s13, s0, 6
	v_cvt_f32_u32_e32 v0, s13
	s_sub_i32 s1, 0, s13
	s_add_i32 s0, s13, 43
	v_rcp_iflag_f32_e32 v0, v0
	s_nop 0
	v_mul_f32_e32 v0, 0x4f7ffffe, v0
	v_cvt_u32_f32_e32 v0, v0
	s_nop 0
	v_readfirstlane_b32 s8, v0
	s_mul_i32 s1, s1, s8
	s_mul_hi_u32 s1, s8, s1
	s_add_i32 s8, s8, s1
	s_mul_hi_u32 s1, s0, s8
	s_mul_i32 s8, s1, s13
	s_sub_i32 s0, s0, s8
	s_add_i32 s9, s1, 1
	s_sub_i32 s8, s0, s13
	s_cmp_ge_u32 s0, s13
	s_cselect_b32 s1, s9, s1
	s_cselect_b32 s0, s8, s0
	s_add_i32 s8, s1, 1
	s_cmp_ge_u32 s0, s13
	s_cselect_b32 s23, s8, s1
	s_mul_i32 s23, s23, 6
	s_cmp_ge_u32 s22, s23
	s_cbranch_scc1 .LBB0_143
	s_cmp_eq_u32 s13, 8
	s_cbranch_scc0 .Lgu_orig1
	s_mov_b32 s63, 0
	s_lshr_b32 s22, s74, 3
	s_movk_i32 s23, 0x88
	s_mov_b64 s[8:9], 0
	s_cmp_lt_u32 s22, 0x80
	s_cbranch_scc0 .Ldec_s1
	s_bfe_u32 s1, s22, 0x50001
	s_lshr_b32 s15, s22, 6
	s_lshl_b32 s15, s15, 5
	s_add_i32 s1, s1, s15
	s_mul_hi_u32 s14, s1, 0x2aaaaaab
	s_mul_i32 s15, s14, 6
	s_sub_i32 s15, s1, s15
	s_lshl_b32 s14, s14, 2
	s_and_b32 s1, s22, 1
	s_lshl_b32 s1, s1, 1
	s_add_i32 s1, s14, s1
	s_branch .Ldec_e1
.Ldec_s1:
	s_add_i32 s1, s22, 0xffffff80
	s_lshr_b32 s15, s1, 2
	s_add_i32 s15, s15, 4
	s_and_b32 s1, s1, 3
	s_add_i32 s1, s1, 40

.LBB0_139:
	s_cmp_eq_u32 s13, 8
	s_cbranch_scc0 .Lgu_orig2
	s_cmp_lt_u32 s22, 0x80
	s_cbranch_scc0 .Ldec_s2
	s_bfe_u32 s1, s22, 0x50001
	s_lshr_b32 s15, s22, 6
	s_lshl_b32 s15, s15, 5
	s_add_i32 s1, s1, s15
	s_mul_hi_u32 s35, s1, 0x2aaaaaab
	s_mul_i32 s15, s35, 6
	s_sub_i32 s15, s1, s15
	s_lshl_b32 s35, s35, 2
	s_and_b32 s1, s22, 1
	s_lshl_b32 s1, s1, 1
	s_add_i32 s1, s35, s1
	s_branch .Ldec_e2
